# P5 and P8: workgroups owning a sample split-K unit run it first (unit order only)
# speedup vs baseline: 1.0016x; 1.0016x over previous
; __device__ __forceinline__ int xcd_map(int L, int nwg) { const int q = nwg / NXCD, r = nwg % NXCD, xcd = L % NXCD, off = L / NXCD; return (xcd < r ? xcd * (q + 1) : r * (q + 1) + (xcd - r) * q) + off; }
;     __device__ __forceinline__ bool next(int i, Unit& u) const { const int L = i * G + c; if (L >= NTOT) return false; pg8::grouped(pg8::xcd_map(L, NTOT), NM, 3, u.pm, u.pn); u.kind = 0; return true; }
;     __device__ __forceinline__ bool next(int i, Unit& u) const { const int L = i * G + c; if (L >= NTOT) return false; pg8::grouped(pg8::xcd_map(L, NTOT), NM, NN, u.pm, u.pn); u.kind = 0; return true; }
;     __device__ __forceinline__ bool next(int i, Unit& u) const {
;         const int L = i * G + c; if (L >= 512 + 8 * nsk) return false;
;         int pm, pn; pg8::grouped(pg8::xcd_map(L < 512 ? L : 0, 512), 128, 4, pm, pn);
;         const int idx = L - 512, rem = idx & 7; const bool sp = L >= 512;
;         u.pm = sp ? 128 + (rem >> 2) : pm; u.pn = sp ? (rem & 3) : pn; u.kind = sp ? 1 + (idx >> 3) : 0;
;         return true;
; __global__ void __launch_bounds__(512, 2) mega_fwd(Args a) {
;     ...
;     {
;         ProgRes<0> P; P.K = 1024; P.lda = 1024; P.ldb = 1024; P.G = G; P.c = bx; P.Ab = YAB; P.Wt = Wt_out; P.xp = x_p; P.Y = out; P.X1 = X1B; P.gate = MOD + 2048; P.part = PART; P.nsk = 4;
;         pg8::gemm_phase(lds, P);
.LBB0_1016:
	s_or_b64 exec, exec, s[0:1]
	s_add_u32 s3, s30, 0x1aa00000
	s_addc_u32 s6, s31, 0
	s_add_u32 s4, s30, 0x15900000
	s_addc_u32 s5, s31, 0
	v_mov_b32_e32 v8, v211
	s_waitcnt lgkmcnt(0)
	s_barrier
	s_mov_b32 s98, s2
	s_cmpk_lt_i32 s2, 0x20
	s_cbranch_scc0 .Lp5_l0
	s_addk_i32 s98, 0x200
.Lp5_l0:
	s_cmpk_gt_i32 s98, 0x21f
	v_readfirstlane_b32 s40, v8
	s_cbranch_scc1 .LBB0_1048
	s_cmpk_lt_i32 s98, 0x200
	s_cselect_b64 s[0:1], -1, 0
	s_and_b64 s[10:11], s[0:1], exec
	s_cselect_b32 s7, s98, 0
	s_ashr_i32 s10, s7, 31
	s_lshr_b32 s10, s10, 29
	s_add_i32 s22, s7, s10
	s_and_b32 s10, s22, -8
	s_sub_i32 s7, s7, s10
	s_cmp_gt_i32 s7, -1
	s_cbranch_scc0 .LBB0_1019
	s_lshl_b32 s21, s7, 6
	s_ashr_i32 s22, s22, 3
	s_cbranch_execz .LBB0_1020
	s_branch .LBB0_1021

; __device__ __forceinline__ int xcd_map(int L, int nwg) { const int q = nwg / NXCD, r = nwg % NXCD, xcd = L % NXCD, off = L / NXCD; return (xcd < r ? xcd * (q + 1) : r * (q + 1) + (xcd - r) * q) + off; }
; template <class Prog>
; __device__ __forceinline__ void gemm_phase(LAS unsigned char* lds, const Prog& P) {
;     ...
;     for (int i = 0; i < 2; ++i) { int R, C; stage_rc(tid * 16 + i * 8192, R, C); const int Rb = (R & ~31) + perm32(R & 31);
;         voffA[i] = (unsigned)(R * lda + C) * 2u; voffB[i] = (unsigned)(Rb * ldb + C) * 2u; }
;     const size_t kstep = (size_t)(BK * 2);
;     const size_t hstepA = (size_t)HALF * lda * 2, hstepB = (size_t)HALF * ldb * 2;
;     const unsigned ldsw = (unsigned)wid * 1024u;
;     const int aoff = lds_byte(wr * 64 + fr, fq * 8), boff = lds_byte(wc * 32 + fr, fq * 8);
;     ...
;     Unit cur, nxt; int ui = 0;
;     if (!P.next(0, cur)) return;
;     f32x4 acc[2][2][4][2];
; #pragma unroll
;     for (int a = 0; a < 2; ++a)
; #pragma unroll
;         for (int b = 0; b < 2; ++b)
; #pragma unroll
;             for (int m = 0; m < 4; ++m)
; #pragma unroll
;                 for (int n = 0; n < 2; ++n) acc[a][b][m][n] = (f32x4){0.f, 0.f, 0.f, 0.f};
;     bf16x8 At[4][2], B0[2][2], B1[2][2];
;     const char* cA = P.aptr(cur); const char* cB = P.bptr(cur);
;     PG8_STAGE(PG8_SB(0, 0), cB, voffB); PG8_STAGE(PG8_SB(0, 1), cB + hstepB, voffB); PG8_STAGE(PG8_SA(0, 0), cA, voffA); PG8_STAGE(PG8_SA(0, 1), cA + hstepA, voffA);
;     if (wr == 1) PG8_BAR;
;     PG8_WAIT_V(2); PG8_BAR;
;     PG8_STAGE(PG8_SB(1, 0), cB + kstep, voffB); PG8_STAGE(PG8_SA(1, 0), cA + kstep, voffA); PG8_STAGE(PG8_SB(1, 1), cB + hstepB + kstep, voffB);
;     PG8_WAIT_V(6); PG8_BAR;
;     __device__ __forceinline__ bool next(int i, Unit& u) const {
;     ...
;         int pm, pn; pg8::grouped(pg8::xcd_map(L < 512 ? L : 0, 512), 128, 4, pm, pn);
;         const int idx = L - 512, rem = idx & 7; const bool sp = L >= 512;
;         u.pm = sp ? 128 + (rem >> 2) : pm; u.pn = sp ? (rem & 3) : pn; u.kind = sp ? 1 + (idx >> 3) : 0;
;         return true;
;     }
;     __device__ __forceinline__ const char* aptr(const Unit& u) const { return (const char*)(Ab + (size_t)u.pm * 256 * K + (u.kind ? (u.kind - 1) * 256 : 0)); }
;     __device__ __forceinline__ const char* bptr(const Unit& u) const { return (const char*)(Wt + (size_t)u.pn * 256 * K + (u.kind ? (u.kind - 1) * 256 : 0)); }
.LBB0_1021:
	v_ashrrev_i32_e32 v1, 31, v8
	v_lshrrev_b32_e32 v1, 26, v1
	v_add_u32_e32 v1, v8, v1
	v_ashrrev_i32_e32 v9, 6, v1
	v_bfe_i32 v1, v8, 27, 1
	v_lshlrev_b32_e32 v0, 4, v8
	v_lshrrev_b32_e32 v1, 22, v1
	v_add_u32_e32 v1, v0, v1
	v_and_b32_e32 v1, 0xfffffc00, v1
	v_sub_u32_e32 v1, v0, v1
	v_lshrrev_b32_e32 v2, 4, v1
	v_bitop3_b32 v2, v2, v1, 32 bitop3:0x6c
	v_ashrrev_i32_e32 v1, 31, v1
	v_lshrrev_b32_e32 v1, 26, v1
	v_add_u32_e32 v1, v2, v1
	v_ashrrev_i32_e32 v10, 6, v1
	v_lshlrev_b32_e32 v3, 3, v9
	v_mul_i32_i24_e32 v4, 64, v10
	v_and_b32_e32 v3, -16, v3
	v_sub_u32_e32 v2, v2, v4
	v_mov_b32_e32 v4, 1
	v_add_u32_e32 v1, v10, v3
	v_lshlrev_b32_e32 v3, 5, v9
	v_ashrrev_i16_sdwa v2, v4, sext(v2) dst_sel:DWORD dst_unused:UNUSED_PAD src0_sel:DWORD src1_sel:BYTE_0
	v_and_b32_e32 v3, 32, v3
	v_bfe_i32 v11, v2, 0, 16
	v_and_b32_e32 v6, 3, v10
	s_mov_b32 s7, 0x1fffe0
	v_add_lshl_u32 v3, v3, v11, 1
	v_add_u32_e32 v0, 0x2000, v0
	v_lshlrev_b32_e32 v2, 1, v1
	v_lshrrev_b32_e32 v5, 2, v1
	v_and_or_b32 v6, v1, s7, v6
	v_lshl_add_u32 v144, v1, 11, v3
	v_ashrrev_i32_e32 v1, 31, v0
	v_lshrrev_b32_e32 v1, 22, v1
	v_add_u32_e32 v1, v0, v1
	s_add_i32 s21, s21, s22
	v_ashrrev_i32_e32 v12, 10, v1
	s_ashr_i32 s22, s21, 31
	v_mul_i32_i24_e32 v1, 0x400, v12
	s_lshr_b32 s22, s22, 27
	v_sub_u32_e32 v0, v0, v1
	s_add_i32 s22, s21, s22
	v_and_b32_e32 v2, 24, v2
	v_and_b32_e32 v5, 4, v5
	v_lshrrev_b32_e32 v1, 4, v0
	s_ashr_i32 s23, s22, 5
	s_and_b32 s22, s22, 0xffe0
	v_or3_b32 v2, v6, v5, v2
	v_bitop3_b32 v0, v1, v0, 32 bitop3:0x6c
	s_sub_i32 s21, s21, s22
	v_lshl_add_u32 v146, v2, 11, v3
	v_ashrrev_i32_e32 v2, 31, v0
	s_bfe_i32 s22, s21, 0x80000
	v_lshrrev_b32_e32 v2, 26, v2
	s_bfe_u32 s22, s22, 0x3000c
	v_add_u32_e32 v2, v0, v2
	s_add_i32 s22, s21, s22
	v_lshlrev_b32_e32 v1, 3, v12
	v_ashrrev_i32_e32 v13, 6, v2
	v_and_b32_e32 v2, 0xc0, v2
	s_bfe_i32 s24, s22, 0x80000
	s_and_b32 s22, s22, 0xf8
	v_and_b32_e32 v1, -16, v1
	v_sub_u32_e32 v0, v0, v2
	s_sub_i32 s21, s21, s22
	v_add_u32_e32 v1, v13, v1
	v_ashrrev_i16_sdwa v0, v4, sext(v0) dst_sel:DWORD dst_unused:UNUSED_PAD src0_sel:DWORD src1_sel:BYTE_0
	v_and_b32_e32 v4, 3, v13
	s_ashr_i32 s11, s40, 6
	s_lshl_b32 s23, s23, 3
	s_sext_i32_i16 s24, s24
	s_sext_i32_i8 s21, s21
	s_bfe_u32 s22, s98, 0x10002
	s_ashr_i32 s10, s40, 8
	v_and_or_b32 v4, v1, s7, v4
	s_lshl_b32 s7, s11, 10
	s_add_i32 s21, s23, s21
	s_ashr_i32 s24, s24, 3
	s_add_i32 s25, s98, 0xfffffe00
	s_or_b32 s26, s22, 0x80
	s_and_b64 s[22:23], s[0:1], exec
	s_cselect_b32 s52, s21, s26
	s_and_b32 s21, s98, 3
	s_and_b64 s[22:23], s[0:1], exec
	s_cselect_b32 s54, s24, s21
	s_lshr_b32 s21, s25, 3
	s_add_i32 s21, s21, 1
	s_and_b64 s[22:23], s[0:1], exec
	s_cselect_b32 s56, 0, s21
	s_lshl_b32 s21, s56, 8
	s_addk_i32 s21, 0xff00
	s_and_b64 s[0:1], s[0:1], exec
	s_cselect_b32 s0, 0, s21
	s_ashr_i32 s53, s52, 31
	s_ashr_i32 s1, s0, 31
	s_lshl_b64 s[22:23], s[52:53], 19
	s_add_u32 s24, s8, s22
	s_addc_u32 s25, s9, s23
	s_ashr_i32 s55, s54, 31
	s_lshl_b64 s[22:23], s[54:55], 19
	v_readlane_b32 s12, v238, 40
	v_readlane_b32 s13, v238, 41
	s_add_u32 s21, s12, s22
	s_addc_u32 s22, s13, s23
	s_lshl_b64 s[0:1], s[0:1], 1
	s_add_u32 s62, s21, s0
	v_lshlrev_b32_e32 v3, 5, v12
	v_bfe_i32 v14, v0, 0, 16
	v_lshlrev_b32_e32 v0, 1, v1
	v_lshrrev_b32_e32 v2, 2, v1
	s_addc_u32 s63, s22, s1
	s_add_i32 s21, s7, 0
	v_and_b32_e32 v3, 32, v3
	v_and_b32_e32 v0, 24, v0
	v_and_b32_e32 v2, 4, v2
	s_add_i32 m0, s21, 0x10000
	v_or3_b32 v0, v4, v2, v0
	v_add_lshl_u32 v2, v3, v14, 1
	global_load_lds_dwordx4 v146, s[62:63]
	s_add_i32 m0, s21, 0x12000
	v_lshl_add_u32 v150, v0, 11, v2
	s_add_u32 s22, s62, 0x40000
	global_load_lds_dwordx4 v150, s[62:63]
	s_addc_u32 s23, s63, 0
	s_add_i32 m0, s21, 0x14000
	v_lshl_add_u32 v148, v1, 11, v2
	global_load_lds_dwordx4 v146, s[22:23]
	s_add_i32 m0, s21, 0x16000
	s_add_u32 s60, s24, s0
	global_load_lds_dwordx4 v150, s[22:23]
	s_addc_u32 s61, s25, s1
	s_add_i32 s22, s21, 0x2000
	s_mov_b32 m0, s21
	s_add_u32 s0, s60, 0x40000
	global_load_lds_dwordx4 v144, s[60:61]
	s_mov_b32 m0, s22
	s_addc_u32 s1, s61, 0
	s_add_i32 s23, s21, 0x4000
	global_load_lds_dwordx4 v148, s[60:61]
	s_mov_b32 m0, s23
	s_add_i32 s24, s21, 0x6000
	global_load_lds_dwordx4 v144, s[0:1]
	s_mov_b32 m0, s24
	v_mov_b32_e32 v147, 0
	global_load_lds_dwordx4 v148, s[0:1]
	v_mov_b32_e32 v151, v147
	v_mov_b32_e32 v145, v147
	v_mov_b32_e32 v149, v147
	s_cmp_eq_u32 s10, 1
	s_mov_b32 s25, 0
	v_lshl_add_u64 v[6:7], s[62:63], 0, v[146:147]
	v_lshl_add_u64 v[4:5], s[62:63], 0, v[150:151]
	v_lshl_add_u64 v[0:1], s[60:61], 0, v[144:145]
	s_cselect_b64 s[36:37], -1, 0
	s_cmp_lg_u32 s10, 1
	v_lshl_add_u64 v[2:3], s[60:61], 0, v[148:149]
	s_cbranch_scc1 .LBB0_1023
	s_barrier

; __device__ __forceinline__ int xcd_map(int L, int nwg) { const int q = nwg / NXCD, r = nwg % NXCD, xcd = L % NXCD, off = L / NXCD; return (xcd < r ? xcd * (q + 1) : r * (q + 1) + (xcd - r) * q) + off; }
;     __device__ __forceinline__ bool next(int i, Unit& u) const { const int L = i * G + c; if (L >= NTOT) return false; pg8::grouped(pg8::xcd_map(L, NTOT), NM, 3, u.pm, u.pn); u.kind = 0; return true; }
;     __device__ __forceinline__ bool next(int i, Unit& u) const { const int L = i * G + c; if (L >= NTOT) return false; pg8::grouped(pg8::xcd_map(L, NTOT), NM, NN, u.pm, u.pn); u.kind = 0; return true; }
;     __device__ __forceinline__ bool next(int i, Unit& u) const {
;         const int L = i * G + c; if (L >= 512 + 8 * nsk) return false;
;         int pm, pn; pg8::grouped(pg8::xcd_map(L < 512 ? L : 0, 512), 128, 4, pm, pn);
;         const int idx = L - 512, rem = idx & 7; const bool sp = L >= 512;
;         u.pm = sp ? 128 + (rem >> 2) : pm; u.pn = sp ? (rem & 3) : pn; u.kind = sp ? 1 + (idx >> 3) : 0;
;         return true;
.LBB0_1026:
	s_add_i32 s25, s25, 1
	s_mul_i32 s43, s25, s34
	s_add_i32 s43, s43, s2
	s_cmpk_lt_i32 s2, 0x20
	s_cbranch_scc0 .Lp5_l1
	s_addk_i32 s43, 0xff00
	s_cmp_lt_i32 s25, 3
	s_cselect_b32 s43, s43, 0x7fff
.Lp5_l1:
	s_cmpk_lt_i32 s43, 0x220
	s_cselect_b64 s[10:11], -1, 0
	s_cmpk_gt_i32 s43, 0x21f
	s_cbranch_scc1 .LBB0_1032
	s_cmpk_lt_i32 s43, 0x200
	s_cselect_b32 s0, s43, 0
	s_ashr_i32 s1, s0, 31
	s_lshr_b32 s1, s1, 29
	s_add_i32 s42, s0, s1
	s_and_b32 s1, s42, -8
	s_sub_i32 s44, s0, s1
	s_cmp_gt_i32 s44, -1
	s_mov_b64 s[0:1], -1
	s_cbranch_scc0 .LBB0_1029
	s_lshl_b32 s45, s44, 6
	s_mov_b64 s[0:1], 0
